# GU/WIN: the first load segment's 16 LDS fragment reads issued at the top of the unit header (latency under the header's scalar arithmetic)
# speedup vs baseline: 1.0112x; 1.0112x over previous
; #define PG8_STAGE(bufoff, gbase, voff) do { _Pragma("unroll") for (int _i = 0; _i < 2; ++_i) \
;         __builtin_amdgcn_global_load_lds((const unsigned*)((const char*)(gbase) + (voff)[_i]), (PG8_LAS unsigned*)(lds + (bufoff) + ldsw + _i * 8192), 16, 0, 0); } while (0)
; #define PG8_LDA(dst, b, h) do { _Pragma("unroll") for (int m = 0; m < 4; ++m) _Pragma("unroll") for (int k = 0; k < 2; ++k) dst[m][k] = *(const PG8_LAS bf16x8*)(lds + PG8_SA(b, h) + aoff + m * 2048 + k * 1024); } while (0)
; #define PG8_LDB(dst, b, h) do { _Pragma("unroll") for (int n = 0; n < 2; ++n) _Pragma("unroll") for (int k = 0; k < 2; ++k) dst[n][k] = *(const PG8_LAS bf16x8*)(lds + PG8_SB(b, h) + boff + n * 2048 + k * 1024); } while (0)
; #define PG8_SCHED __builtin_amdgcn_sched_barrier(0)
;     __host__ __device__ bool next(int i, Unit& u) const {
;         const long L = (long)i * G + c; if (L >= nwg) return false;
;         int wgid = (int)L; { const int q = nwg / NXCD, r = nwg % NXCD, xcd = wgid % NXCD, off = wgid / NXCD; wgid = (xcd < r ? xcd * (q + 1) : r * (q + 1) + (xcd - r) * q) + off; }
;         const int nig = WGM * nN, gid = wgid / nig, fm = gid * WGM, gsz = (nM - fm) < WGM ? (nM - fm) : WGM;
;         u.pm = fm + ((wgid % nig) % gsz); u.pn = (wgid % nig) / gsz; return true;
;     }
; template <class Epi, class Sched, bool ALIGN_EPI = false, bool SP2 = false>
; __device__ __forceinline__ void gemm_phase(PG8_LAS unsigned char* lds, const Gemm g, const Sched& S, const Epi& E) {
;     ...
;             PG8_LDB(B0, 0, 0); PG8_LDB(B1, 0, 1); PG8_SCHED; PG8_LDA(At, 0, 0); PG8_STAGE(PG8_SA(1, 1), a1 + hstep, voffA);
.LBB0_241:
	s_add_i32 s59, 0, 0x10000
	v_add_u32_e32 v144, s59, v197
	s_add_i32 s62, 0, 0x14000
	ds_read_b128 v[132:135], v144
	ds_read_b128 v[136:139], v144 offset:1024
	ds_read_b128 v[140:143], v144 offset:2048
	ds_read_b128 v[202:205], v144 offset:3072
	v_add_u32_e32 v144, s62, v197
	ds_read_b128 v[206:209], v144
	ds_read_b128 v[210:213], v144 offset:1024
	ds_read_b128 v[214:217], v144 offset:2048
	ds_read_b128 v[218:221], v144 offset:3072
	ds_read_b128 v[222:225], v199
	ds_read_b128 v[226:229], v199 offset:1024
	ds_read_b128 v[230:233], v199 offset:2048
	ds_read_b128 v[234:237], v199 offset:3072
	ds_read_b128 v[238:241], v199 offset:4096
	ds_read_b128 v[242:245], v199 offset:5120
	ds_read_b128 v[246:249], v199 offset:6144
	ds_read_b128 v[180:183], v199 offset:7168
	s_add_i32 s34, s34, 1
	s_mul_i32 s6, s34, s23
	s_mul_hi_u32 s7, s34, s22
	s_add_i32 s7, s7, s6
	s_mul_i32 s6, s34, s22
	s_add_u32 s6, s6, s89
	s_addc_u32 s7, s7, s13
	v_mov_b64_e32 v[0:1], 0x2c0
	v_cmp_lt_i64_e64 s[36:37], s[6:7], v[0:1]
	v_mov_b64_e32 v[0:1], 0x2bf
	v_cmp_gt_i64_e32 vcc, s[6:7], v[0:1]
	s_cbranch_vccnz .LBB0_243
	s_ashr_i32 s7, s6, 31
	s_lshr_b32 s7, s7, 29
	s_add_i32 s7, s6, s7
	s_ashr_i32 s38, s7, 3
	s_and_b32 s7, s7, -8
	s_sub_i32 s6, s6, s7
	s_cmp_lt_i32 s6, 0
	s_cselect_b32 s7, s88, 0x58
	s_mul_i32 s6, s6, s7
	s_add_i32 s6, s6, s38
	s_mul_hi_i32 s7, s6, 0x2e8ba2e9
	s_lshr_b32 s38, s7, 31
	s_ashr_i32 s7, s7, 3
	s_add_i32 s7, s7, s38
	s_lshl_b32 s38, s7, 2
	s_sub_i32 s39, 64, s38
	s_min_i32 s39, s39, 4
	s_abs_i32 s46, s39
	v_cvt_f32_u32_e32 v0, s46
	s_sub_i32 s48, 0, s46
	s_mul_i32 s7, s7, 44
	s_sub_i32 s6, s6, s7
	v_rcp_iflag_f32_e32 v0, v0
	s_abs_i32 s7, s6
	s_xor_b32 s47, s6, s39
	s_ashr_i32 s47, s47, 31
	v_mul_f32_e32 v0, 0x4f7ffffe, v0
	v_cvt_u32_f32_e32 v0, v0
	s_nop 0
	v_readfirstlane_b32 s49, v0
	s_mul_i32 s48, s48, s49
	s_mul_hi_u32 s48, s49, s48
	s_add_i32 s49, s49, s48
	s_mul_hi_u32 s48, s7, s49
	s_mul_i32 s49, s48, s46
	s_sub_i32 s7, s7, s49
	s_add_i32 s50, s48, 1
	s_sub_i32 s49, s7, s46
	s_cmp_ge_u32 s7, s46
	s_cselect_b32 s48, s50, s48
	s_cselect_b32 s7, s49, s7
	s_add_i32 s49, s48, 1
	s_cmp_ge_u32 s7, s46
	s_cselect_b32 s7, s49, s48
	s_xor_b32 s7, s7, s47
	s_sub_i32 s46, s7, s47
	s_mul_i32 s7, s46, s39
	s_sub_i32 s6, s6, s7
	s_add_i32 s48, s38, s6

; #define PG8_STAGE(bufoff, gbase, voff) do { _Pragma("unroll") for (int _i = 0; _i < 2; ++_i) \
;         __builtin_amdgcn_global_load_lds((const unsigned*)((const char*)(gbase) + (voff)[_i]), (PG8_LAS unsigned*)(lds + (bufoff) + ldsw + _i * 8192), 16, 0, 0); } while (0)
; #define PG8_LDA(dst, b, h) do { _Pragma("unroll") for (int m = 0; m < 4; ++m) _Pragma("unroll") for (int k = 0; k < 2; ++k) dst[m][k] = *(const PG8_LAS bf16x8*)(lds + PG8_SA(b, h) + aoff + m * 2048 + k * 1024); } while (0)
; #define PG8_LDB(dst, b, h) do { _Pragma("unroll") for (int n = 0; n < 2; ++n) _Pragma("unroll") for (int k = 0; k < 2; ++k) dst[n][k] = *(const PG8_LAS bf16x8*)(lds + PG8_SB(b, h) + boff + n * 2048 + k * 1024); } while (0)
; #define PG8_MMA(ai, bj, At, Bt) do { __builtin_amdgcn_s_setprio(1); _Pragma("unroll") for (int m = 0; m < 4; ++m) _Pragma("unroll") for (int n = 0; n < 2; ++n) _Pragma("unroll") for (int k = 0; k < 2; ++k) \
;         acc[ai][bj][m][n] = __builtin_amdgcn_mfma_f32_16x16x32_bf16(Bt[n][k], At[m][k], acc[ai][bj][m][n], 0, 0, 0); __builtin_amdgcn_s_setprio(0); } while (0)
; #define PG8_WAIT_V(n) asm volatile("s_waitcnt vmcnt(" #n ")" ::: "memory")
; #define PG8_WAIT_L(n) asm volatile("s_waitcnt lgkmcnt(" #n ")" ::: "memory")
; #define PG8_BAR __builtin_amdgcn_s_barrier()
; #define PG8_SCHED __builtin_amdgcn_sched_barrier(0)
; template <class Epi, class Sched, bool ALIGN_EPI = false, bool SP2 = false>
; __device__ __forceinline__ void gemm_phase(PG8_LAS unsigned char* lds, const Gemm g, const Sched& S, const Epi& E) {
;     ...
;             PG8_LDB(B0, 0, 0); PG8_LDB(B1, 0, 1); PG8_SCHED; PG8_LDA(At, 0, 0); PG8_STAGE(PG8_SA(1, 1), a1 + hstep, voffA);
;             PG8_WAIT_V(8); PG8_WAIT_L(0); PG8_BAR; PG8_MMA(0, 0, At, B0); PG8_MMA(0, 1, At, B1); PG8_BAR; PG8_SCHED;
;             PG8_LDA(At, 0, 1); PG8_STAGE(PG8_SB(0, 0), b2, voffB); PG8_STAGE(PG8_SB(0, 1), b2 + hstep, voffB); PG8_STAGE(PG8_SA(0, 0), a2, voffA);
;             PG8_WAIT_V(8); PG8_WAIT_L(0); PG8_BAR; PG8_MMA(1, 0, At, B0); PG8_MMA(1, 1, At, B1); PG8_BAR; PG8_SCHED;
.Lwin_peel:
	s_mov_b64 s[0:1], 0
	s_add_u32 s6, s4, 0xfffc0080
	s_addc_u32 s7, s5, -1
	s_and_b64 s[0:1], s[0:1], exec
	s_cselect_b32 s7, s38, s7
	s_cselect_b32 s6, s39, s6
	s_cselect_b32 s1, s49, s57
	s_cselect_b32 s0, s55, s56
	s_add_i32 s59, 0, 0x10000
	s_add_i32 s62, 0, 0x14000
	v_lshl_add_u64 v[172:173], s[4:5], 0, v[166:167]
	s_add_i32 m0, s25, 0xc000
	global_load_lds_dwordx4 v[172:173], off
	v_lshl_add_u64 v[172:173], s[4:5], 0, v[168:169]
	s_add_i32 m0, s25, 0xe000
	s_nop 0
	global_load_lds_dwordx4 v[172:173], off
	s_waitcnt vmcnt(8)
	s_waitcnt lgkmcnt(0)
	.p2alignl 3, 3212836864
	s_setprio 1
	s_barrier
	v_mfma_f32_16x16x32_bf16 v[124:127], v[132:135], v[222:225], 0
	v_mfma_f32_16x16x32_bf16 v[120:123], v[140:143], v[222:225], 0
	v_mfma_f32_16x16x32_bf16 v[108:111], v[132:135], v[230:233], 0
	v_mfma_f32_16x16x32_bf16 v[104:107], v[140:143], v[230:233], 0
	v_mfma_f32_16x16x32_bf16 v[92:95], v[132:135], v[238:241], 0
	v_mfma_f32_16x16x32_bf16 v[88:91], v[140:143], v[238:241], 0
	v_mfma_f32_16x16x32_bf16 v[76:79], v[132:135], v[246:249], 0
	v_mfma_f32_16x16x32_bf16 v[72:75], v[140:143], v[246:249], 0
	v_mfma_f32_16x16x32_bf16 v[124:127], v[136:139], v[226:229], v[124:127]
	v_mfma_f32_16x16x32_bf16 v[120:123], v[202:205], v[226:229], v[120:123]
	v_mfma_f32_16x16x32_bf16 v[108:111], v[136:139], v[234:237], v[108:111]
	v_mfma_f32_16x16x32_bf16 v[104:107], v[202:205], v[234:237], v[104:107]
	v_mfma_f32_16x16x32_bf16 v[92:95], v[136:139], v[242:245], v[92:95]
	v_mfma_f32_16x16x32_bf16 v[88:91], v[202:205], v[242:245], v[88:91]
	v_mfma_f32_16x16x32_bf16 v[76:79], v[136:139], v[180:183], v[76:79]
	v_mfma_f32_16x16x32_bf16 v[72:75], v[202:205], v[180:183], v[72:75]
	s_setprio 0
	s_setprio 1
	v_mfma_f32_16x16x32_bf16 v[116:119], v[206:209], v[222:225], 0
	v_mfma_f32_16x16x32_bf16 v[112:115], v[214:217], v[222:225], 0
	v_mfma_f32_16x16x32_bf16 v[100:103], v[206:209], v[230:233], 0
	v_mfma_f32_16x16x32_bf16 v[96:99], v[214:217], v[230:233], 0
	v_mfma_f32_16x16x32_bf16 v[84:87], v[206:209], v[238:241], 0
	v_mfma_f32_16x16x32_bf16 v[80:83], v[214:217], v[238:241], 0
	v_mfma_f32_16x16x32_bf16 v[68:71], v[206:209], v[246:249], 0
	v_mfma_f32_16x16x32_bf16 v[64:67], v[214:217], v[246:249], 0
	v_mfma_f32_16x16x32_bf16 v[116:119], v[210:213], v[226:229], v[116:119]
	v_mfma_f32_16x16x32_bf16 v[112:115], v[218:221], v[226:229], v[112:115]
	v_mfma_f32_16x16x32_bf16 v[100:103], v[210:213], v[234:237], v[100:103]
	v_mfma_f32_16x16x32_bf16 v[96:99], v[218:221], v[234:237], v[96:99]
	v_mfma_f32_16x16x32_bf16 v[84:87], v[210:213], v[242:245], v[84:87]
	v_mfma_f32_16x16x32_bf16 v[80:83], v[218:221], v[242:245], v[80:83]
	v_mfma_f32_16x16x32_bf16 v[68:71], v[210:213], v[180:183], v[68:71]
	v_mfma_f32_16x16x32_bf16 v[64:67], v[218:221], v[180:183], v[64:67]
	s_barrier
	s_setprio 0
	s_add_i32 s59, s59, s24
	v_lshl_add_u64 v[172:173], s[0:1], 0, v[154:155]
	s_mov_b32 m0, s59
	ds_read_b128 v[180:183], v199 offset:16384
	ds_read_b128 v[222:225], v199 offset:17408
	ds_read_b128 v[226:229], v199 offset:18432
	ds_read_b128 v[230:233], v199 offset:19456
	ds_read_b128 v[234:237], v199 offset:20480
	ds_read_b128 v[238:241], v199 offset:21504
	ds_read_b128 v[242:245], v199 offset:22528
	ds_read_b128 v[246:249], v199 offset:23552
	global_load_lds_dwordx4 v[172:173], off
	s_add_i32 m0, s59, 0x2000
	s_add_u32 s60, s0, 0x40000
	v_lshl_add_u64 v[184:185], s[0:1], 0, v[150:151]
	s_addc_u32 s61, s1, 0
	s_add_i32 s59, s62, s24
	global_load_lds_dwordx4 v[184:185], off
	v_lshl_add_u64 v[186:187], s[60:61], 0, v[154:155]
	s_mov_b32 m0, s59
	v_lshl_add_u64 v[188:189], s[6:7], 0, v[152:153]
	global_load_lds_dwordx4 v[186:187], off
	v_lshl_add_u64 v[186:187], s[60:61], 0, v[150:151]
	s_add_i32 m0, s59, 0x2000
	s_nop 0
	global_load_lds_dwordx4 v[186:187], off
	v_lshl_add_u64 v[186:187], s[6:7], 0, v[156:157]
	s_mov_b32 m0, s25
	s_nop 0
	global_load_lds_dwordx4 v[186:187], off
	s_mov_b32 m0, s26
	s_nop 0
	global_load_lds_dwordx4 v[188:189], off
	s_waitcnt vmcnt(8)
	s_waitcnt lgkmcnt(0)
	.p2alignl 3, 3212836864
	s_setprio 1
	s_barrier
	v_mfma_f32_16x16x32_bf16 v[60:63], v[132:135], v[180:183], 0
	v_mfma_f32_16x16x32_bf16 v[56:59], v[140:143], v[180:183], 0
	v_mfma_f32_16x16x32_bf16 v[44:47], v[132:135], v[226:229], 0
	v_mfma_f32_16x16x32_bf16 v[40:43], v[140:143], v[226:229], 0
	v_mfma_f32_16x16x32_bf16 v[28:31], v[132:135], v[234:237], 0
	v_mfma_f32_16x16x32_bf16 v[24:27], v[140:143], v[234:237], 0
	v_mfma_f32_16x16x32_bf16 v[12:15], v[132:135], v[242:245], 0
	v_mfma_f32_16x16x32_bf16 v[8:11], v[140:143], v[242:245], 0
	v_mfma_f32_16x16x32_bf16 v[60:63], v[136:139], v[222:225], v[60:63]
	v_mfma_f32_16x16x32_bf16 v[56:59], v[202:205], v[222:225], v[56:59]
	v_mfma_f32_16x16x32_bf16 v[44:47], v[136:139], v[230:233], v[44:47]
	v_mfma_f32_16x16x32_bf16 v[40:43], v[202:205], v[230:233], v[40:43]
	v_mfma_f32_16x16x32_bf16 v[28:31], v[136:139], v[238:241], v[28:31]
	v_mfma_f32_16x16x32_bf16 v[24:27], v[202:205], v[238:241], v[24:27]
	v_mfma_f32_16x16x32_bf16 v[12:15], v[136:139], v[246:249], v[12:15]
	v_mfma_f32_16x16x32_bf16 v[8:11], v[202:205], v[246:249], v[8:11]
	s_setprio 0
	s_setprio 1
	v_mfma_f32_16x16x32_bf16 v[52:55], v[206:209], v[180:183], 0
	v_mfma_f32_16x16x32_bf16 v[48:51], v[214:217], v[180:183], 0
	v_mfma_f32_16x16x32_bf16 v[36:39], v[206:209], v[226:229], 0
	v_mfma_f32_16x16x32_bf16 v[32:35], v[214:217], v[226:229], 0
	v_mfma_f32_16x16x32_bf16 v[20:23], v[206:209], v[234:237], 0
	v_mfma_f32_16x16x32_bf16 v[16:19], v[214:217], v[234:237], 0
	v_mfma_f32_16x16x32_bf16 v[4:7], v[206:209], v[242:245], 0
	v_mfma_f32_16x16x32_bf16 v[0:3], v[214:217], v[242:245], 0
	v_mfma_f32_16x16x32_bf16 v[52:55], v[210:213], v[222:225], v[52:55]
	v_mfma_f32_16x16x32_bf16 v[48:51], v[218:221], v[222:225], v[48:51]
	v_mfma_f32_16x16x32_bf16 v[36:39], v[210:213], v[230:233], v[36:39]
	v_mfma_f32_16x16x32_bf16 v[32:35], v[218:221], v[230:233], v[32:35]
	v_mfma_f32_16x16x32_bf16 v[20:23], v[210:213], v[238:241], v[20:23]
	v_mfma_f32_16x16x32_bf16 v[16:19], v[218:221], v[238:241], v[16:19]
	v_mfma_f32_16x16x32_bf16 v[4:7], v[210:213], v[246:249], v[4:7]
	v_mfma_f32_16x16x32_bf16 v[0:3], v[218:221], v[246:249], v[0:3]
	s_barrier
; #define PG8_STAGE(bufoff, gbase, voff) do { _Pragma("unroll") for (int _i = 0; _i < 2; ++_i) \
;         __builtin_amdgcn_global_load_lds((const unsigned*)((const char*)(gbase) + (voff)[_i]), (PG8_LAS unsigned*)(lds + (bufoff) + ldsw + _i * 8192), 16, 0, 0); } while (0)
; #define PG8_LDA(dst, b, h) do { _Pragma("unroll") for (int m = 0; m < 4; ++m) _Pragma("unroll") for (int k = 0; k < 2; ++k) dst[m][k] = *(const PG8_LAS bf16x8*)(lds + PG8_SA(b, h) + aoff + m * 2048 + k * 1024); } while (0)
; #define PG8_LDB(dst, b, h) do { _Pragma("unroll") for (int n = 0; n < 2; ++n) _Pragma("unroll") for (int k = 0; k < 2; ++k) dst[n][k] = *(const PG8_LAS bf16x8*)(lds + PG8_SB(b, h) + boff + n * 2048 + k * 1024); } while (0)
; #define PG8_MMA(ai, bj, At, Bt) do { __builtin_amdgcn_s_setprio(1); _Pragma("unroll") for (int m = 0; m < 4; ++m) _Pragma("unroll") for (int n = 0; n < 2; ++n) _Pragma("unroll") for (int k = 0; k < 2; ++k) \
;         acc[ai][bj][m][n] = __builtin_amdgcn_mfma_f32_16x16x32_bf16(Bt[n][k], At[m][k], acc[ai][bj][m][n], 0, 0, 0); __builtin_amdgcn_s_setprio(0); } while (0)
; #define PG8_WAIT_V(n) asm volatile("s_waitcnt vmcnt(" #n ")" ::: "memory")
; #define PG8_WAIT_L(n) asm volatile("s_waitcnt lgkmcnt(" #n ")" ::: "memory")
; #define PG8_BAR __builtin_amdgcn_s_barrier()
; #define PG8_SCHED __builtin_amdgcn_sched_barrier(0)
; template <class Epi, class Sched, bool ALIGN_EPI = false, bool SP2 = false>
; __device__ __forceinline__ void gemm_phase(PG8_LAS unsigned char* lds, const Gemm g, const Sched& S, const Epi& E) {
;     ...
;             PG8_LDB(B0, 1, 0); PG8_LDB(B1, 1, 1); PG8_SCHED; PG8_LDA(At, 1, 0); PG8_STAGE(PG8_SA(0, 1), a2 + hstep, voffA);
;             PG8_WAIT_V(8); PG8_WAIT_L(0); PG8_BAR; PG8_MMA(0, 0, At, B0); PG8_MMA(0, 1, At, B1); PG8_BAR; PG8_SCHED;
	s_setprio 0
	s_add_i32 s59, 0, 0x18000
	v_add_u32_e32 v144, s59, v197
	s_add_i32 s60, 0, 0x1c000
	ds_read_b128 v[132:135], v144
	ds_read_b128 v[136:139], v144 offset:1024
	ds_read_b128 v[140:143], v144 offset:2048
	ds_read_b128 v[180:183], v144 offset:3072
	v_add_u32_e32 v144, s60, v197
	ds_read_b128 v[202:205], v144
	ds_read_b128 v[206:209], v144 offset:1024
	ds_read_b128 v[210:213], v144 offset:2048
	ds_read_b128 v[214:217], v144 offset:3072
	s_add_u32 s6, s6, 0x40000
	s_addc_u32 s7, s7, 0
	s_mov_b32 m0, s27
	v_lshl_add_u64 v[190:191], s[6:7], 0, v[156:157]
	ds_read_b128 v[218:221], v199 offset:32768
	ds_read_b128 v[222:225], v199 offset:33792
	ds_read_b128 v[226:229], v199 offset:34816
	ds_read_b128 v[230:233], v199 offset:35840
	ds_read_b128 v[234:237], v199 offset:36864
	ds_read_b128 v[238:241], v199 offset:37888
	ds_read_b128 v[242:245], v199 offset:38912
	ds_read_b128 v[246:249], v199 offset:39936
	global_load_lds_dwordx4 v[190:191], off
	v_lshl_add_u64 v[190:191], s[6:7], 0, v[152:153]
	s_mov_b32 m0, s28
	s_nop 0
	global_load_lds_dwordx4 v[190:191], off
	s_waitcnt vmcnt(8)
	s_waitcnt lgkmcnt(0)
	.p2alignl 3, 3212836864
	s_setprio 1
	s_barrier
	v_mfma_f32_16x16x32_bf16 v[124:127], v[132:135], v[218:221], v[124:127]
	v_mfma_f32_16x16x32_bf16 v[120:123], v[140:143], v[218:221], v[120:123]
	v_mfma_f32_16x16x32_bf16 v[108:111], v[132:135], v[226:229], v[108:111]
	v_mfma_f32_16x16x32_bf16 v[104:107], v[140:143], v[226:229], v[104:107]
	v_mfma_f32_16x16x32_bf16 v[92:95], v[132:135], v[234:237], v[92:95]
	v_mfma_f32_16x16x32_bf16 v[88:91], v[140:143], v[234:237], v[88:91]
	v_mfma_f32_16x16x32_bf16 v[76:79], v[132:135], v[242:245], v[76:79]
	v_mfma_f32_16x16x32_bf16 v[72:75], v[140:143], v[242:245], v[72:75]
	v_mfma_f32_16x16x32_bf16 v[124:127], v[136:139], v[222:225], v[124:127]
	v_mfma_f32_16x16x32_bf16 v[120:123], v[180:183], v[222:225], v[120:123]
	v_mfma_f32_16x16x32_bf16 v[108:111], v[136:139], v[230:233], v[108:111]
	v_mfma_f32_16x16x32_bf16 v[104:107], v[180:183], v[230:233], v[104:107]
	v_mfma_f32_16x16x32_bf16 v[92:95], v[136:139], v[238:241], v[92:95]
	v_mfma_f32_16x16x32_bf16 v[88:91], v[180:183], v[238:241], v[88:91]
	v_mfma_f32_16x16x32_bf16 v[76:79], v[136:139], v[246:249], v[76:79]
	v_mfma_f32_16x16x32_bf16 v[72:75], v[180:183], v[246:249], v[72:75]
	s_setprio 0
	s_setprio 1
	v_mfma_f32_16x16x32_bf16 v[116:119], v[202:205], v[218:221], v[116:119]
	v_mfma_f32_16x16x32_bf16 v[112:115], v[210:213], v[218:221], v[112:115]
	v_mfma_f32_16x16x32_bf16 v[100:103], v[202:205], v[226:229], v[100:103]
	v_mfma_f32_16x16x32_bf16 v[96:99], v[210:213], v[226:229], v[96:99]
	v_mfma_f32_16x16x32_bf16 v[84:87], v[202:205], v[234:237], v[84:87]
	v_mfma_f32_16x16x32_bf16 v[80:83], v[210:213], v[234:237], v[80:83]
	v_mfma_f32_16x16x32_bf16 v[68:71], v[202:205], v[242:245], v[68:71]
	v_mfma_f32_16x16x32_bf16 v[64:67], v[210:213], v[242:245], v[64:67]
	v_mfma_f32_16x16x32_bf16 v[116:119], v[206:209], v[222:225], v[116:119]
	v_mfma_f32_16x16x32_bf16 v[112:115], v[214:217], v[222:225], v[112:115]
	v_mfma_f32_16x16x32_bf16 v[100:103], v[206:209], v[230:233], v[100:103]
	v_mfma_f32_16x16x32_bf16 v[96:99], v[214:217], v[230:233], v[96:99]
	v_mfma_f32_16x16x32_bf16 v[84:87], v[206:209], v[238:241], v[84:87]
	v_mfma_f32_16x16x32_bf16 v[80:83], v[214:217], v[238:241], v[80:83]
	v_mfma_f32_16x16x32_bf16 v[68:71], v[206:209], v[246:249], v[68:71]
	v_mfma_f32_16x16x32_bf16 v[64:67], v[214:217], v[246:249], v[64:67]
	s_barrier
; #define PG8_STAGE(bufoff, gbase, voff) do { _Pragma("unroll") for (int _i = 0; _i < 2; ++_i) \
;         __builtin_amdgcn_global_load_lds((const unsigned*)((const char*)(gbase) + (voff)[_i]), (PG8_LAS unsigned*)(lds + (bufoff) + ldsw + _i * 8192), 16, 0, 0); } while (0)
; #define PG8_LDA(dst, b, h) do { _Pragma("unroll") for (int m = 0; m < 4; ++m) _Pragma("unroll") for (int k = 0; k < 2; ++k) dst[m][k] = *(const PG8_LAS bf16x8*)(lds + PG8_SA(b, h) + aoff + m * 2048 + k * 1024); } while (0)
; #define PG8_MMA(ai, bj, At, Bt) do { __builtin_amdgcn_s_setprio(1); _Pragma("unroll") for (int m = 0; m < 4; ++m) _Pragma("unroll") for (int n = 0; n < 2; ++n) _Pragma("unroll") for (int k = 0; k < 2; ++k) \
;         acc[ai][bj][m][n] = __builtin_amdgcn_mfma_f32_16x16x32_bf16(Bt[n][k], At[m][k], acc[ai][bj][m][n], 0, 0, 0); __builtin_amdgcn_s_setprio(0); } while (0)
; #define PG8_WAIT_V(n) asm volatile("s_waitcnt vmcnt(" #n ")" ::: "memory")
; #define PG8_WAIT_L(n) asm volatile("s_waitcnt lgkmcnt(" #n ")" ::: "memory")
; #define PG8_BAR __builtin_amdgcn_s_barrier()
; #define PG8_SCHED __builtin_amdgcn_sched_barrier(0)
; template <class Epi, class Sched, bool ALIGN_EPI = false, bool SP2 = false>
; __device__ __forceinline__ void gemm_phase(PG8_LAS unsigned char* lds, const Gemm g, const Sched& S, const Epi& E) {
;     ...
;         for (int t = 0; t < nt; t += 2) {
;     ...
;             PG8_LDA(At, 1, 1); PG8_STAGE(PG8_SB(1, 0), b3, voffB); PG8_STAGE(PG8_SB(1, 1), b3 + hstep, voffB); PG8_STAGE(PG8_SA(1, 0), a3, voffA);
;             PG8_WAIT_V(8); PG8_WAIT_L(0); PG8_BAR; PG8_MMA(1, 0, At, B0); PG8_MMA(1, 1, At, B1); PG8_BAR; PG8_SCHED;
	s_setprio 0
	s_add_i32 s6, s59, s24
	v_lshl_add_u64 v[172:173], v[172:173], 0, s[94:95]
	s_mov_b32 m0, s6
	ds_read_b128 v[218:221], v199 offset:49152
	ds_read_b128 v[222:225], v199 offset:50176
	ds_read_b128 v[226:229], v199 offset:51200
	ds_read_b128 v[230:233], v199 offset:52224
	ds_read_b128 v[234:237], v199 offset:53248
	ds_read_b128 v[238:241], v199 offset:54272
	ds_read_b128 v[242:245], v199 offset:55296
	ds_read_b128 v[246:249], v199 offset:56320
	global_load_lds_dwordx4 v[172:173], off
	s_add_i32 m0, s6, 0x2000
	s_add_u32 s0, s0, 0x40080
	v_lshl_add_u64 v[172:173], v[184:185], 0, s[94:95]
	s_addc_u32 s1, s1, 0
	s_add_i32 s6, s60, s24
	global_load_lds_dwordx4 v[172:173], off
	v_lshl_add_u64 v[172:173], s[0:1], 0, v[154:155]
	s_mov_b32 m0, s6
	s_nop 0
	global_load_lds_dwordx4 v[172:173], off
	v_lshl_add_u64 v[172:173], s[0:1], 0, v[150:151]
	s_add_i32 m0, s6, 0x2000
	s_nop 0
	global_load_lds_dwordx4 v[172:173], off
	v_lshl_add_u64 v[172:173], v[186:187], 0, s[94:95]
	s_mov_b32 m0, s29
	s_nop 0
	global_load_lds_dwordx4 v[172:173], off
	v_lshl_add_u64 v[172:173], v[188:189], 0, s[94:95]
	s_mov_b32 m0, s30
	s_nop 0
	global_load_lds_dwordx4 v[172:173], off
	s_waitcnt vmcnt(8)
	s_waitcnt lgkmcnt(0)
	.p2alignl 3, 3212836864
	s_setprio 1
	s_barrier
	v_mfma_f32_16x16x32_bf16 v[60:63], v[132:135], v[218:221], v[60:63]
	v_mfma_f32_16x16x32_bf16 v[56:59], v[140:143], v[218:221], v[56:59]
	v_mfma_f32_16x16x32_bf16 v[44:47], v[132:135], v[226:229], v[44:47]
	v_mfma_f32_16x16x32_bf16 v[40:43], v[140:143], v[226:229], v[40:43]
	v_mfma_f32_16x16x32_bf16 v[28:31], v[132:135], v[234:237], v[28:31]
	v_mfma_f32_16x16x32_bf16 v[24:27], v[140:143], v[234:237], v[24:27]
	v_mfma_f32_16x16x32_bf16 v[12:15], v[132:135], v[242:245], v[12:15]
	v_mfma_f32_16x16x32_bf16 v[8:11], v[140:143], v[242:245], v[8:11]
	v_mfma_f32_16x16x32_bf16 v[60:63], v[136:139], v[222:225], v[60:63]
	v_mfma_f32_16x16x32_bf16 v[56:59], v[180:183], v[222:225], v[56:59]
	v_mfma_f32_16x16x32_bf16 v[44:47], v[136:139], v[230:233], v[44:47]
	v_mfma_f32_16x16x32_bf16 v[40:43], v[180:183], v[230:233], v[40:43]
	v_mfma_f32_16x16x32_bf16 v[28:31], v[136:139], v[238:241], v[28:31]
	v_mfma_f32_16x16x32_bf16 v[24:27], v[180:183], v[238:241], v[24:27]
	v_mfma_f32_16x16x32_bf16 v[12:15], v[136:139], v[246:249], v[12:15]
	v_mfma_f32_16x16x32_bf16 v[8:11], v[180:183], v[246:249], v[8:11]
	s_setprio 0
	s_setprio 1
	v_mfma_f32_16x16x32_bf16 v[52:55], v[202:205], v[218:221], v[52:55]
	v_mfma_f32_16x16x32_bf16 v[48:51], v[210:213], v[218:221], v[48:51]
	v_mfma_f32_16x16x32_bf16 v[36:39], v[202:205], v[226:229], v[36:39]
	v_mfma_f32_16x16x32_bf16 v[32:35], v[210:213], v[226:229], v[32:35]
	v_mfma_f32_16x16x32_bf16 v[20:23], v[202:205], v[234:237], v[20:23]
	v_mfma_f32_16x16x32_bf16 v[16:19], v[210:213], v[234:237], v[16:19]
	v_mfma_f32_16x16x32_bf16 v[4:7], v[202:205], v[242:245], v[4:7]
	v_mfma_f32_16x16x32_bf16 v[0:3], v[210:213], v[242:245], v[0:3]
	v_mfma_f32_16x16x32_bf16 v[52:55], v[206:209], v[222:225], v[52:55]
	v_mfma_f32_16x16x32_bf16 v[48:51], v[214:217], v[222:225], v[48:51]
	v_mfma_f32_16x16x32_bf16 v[36:39], v[206:209], v[230:233], v[36:39]
	v_mfma_f32_16x16x32_bf16 v[32:35], v[214:217], v[230:233], v[32:35]
	v_mfma_f32_16x16x32_bf16 v[20:23], v[206:209], v[238:241], v[20:23]
	v_mfma_f32_16x16x32_bf16 v[16:19], v[214:217], v[238:241], v[16:19]
	v_mfma_f32_16x16x32_bf16 v[4:7], v[206:209], v[246:249], v[4:7]
	v_mfma_f32_16x16x32_bf16 v[0:3], v[214:217], v[246:249], v[0:3]
	s_barrier
	s_setprio 0
	s_add_i32 s58, s58, 2
	s_add_u32 s4, s4, 0x100
	s_addc_u32 s5, s5, 0
	s_add_u32 s56, s56, 0x100
	s_addc_u32 s57, s57, 0
	s_cmp_gt_u32 s58, 13
	s_branch .LBB0_245

; #define PG8_STAGE(bufoff, gbase, voff) do { _Pragma("unroll") for (int _i = 0; _i < 2; ++_i) \
;         __builtin_amdgcn_global_load_lds((const unsigned*)((const char*)(gbase) + (voff)[_i]), (PG8_LAS unsigned*)(lds + (bufoff) + ldsw + _i * 8192), 16, 0, 0); } while (0)
; #define PG8_LDA(dst, b, h) do { _Pragma("unroll") for (int m = 0; m < 4; ++m) _Pragma("unroll") for (int k = 0; k < 2; ++k) dst[m][k] = *(const PG8_LAS bf16x8*)(lds + PG8_SA(b, h) + aoff + m * 2048 + k * 1024); } while (0)
; #define PG8_LDB(dst, b, h) do { _Pragma("unroll") for (int n = 0; n < 2; ++n) _Pragma("unroll") for (int k = 0; k < 2; ++k) dst[n][k] = *(const PG8_LAS bf16x8*)(lds + PG8_SB(b, h) + boff + n * 2048 + k * 1024); } while (0)
; #define PG8_SCHED __builtin_amdgcn_sched_barrier(0)
;     __host__ __device__ bool next(int i, Unit& u) const {
;         const long L = (long)i * G + c; if (L >= nwg) return false;
;         int wgid = (int)L; { const int q = nwg / NXCD, r = nwg % NXCD, xcd = wgid % NXCD, off = wgid / NXCD; wgid = (xcd < r ? xcd * (q + 1) : r * (q + 1) + (xcd - r) * q) + off; }
;         const int nig = WGM * nN, gid = wgid / nig, fm = gid * WGM, gsz = (nM - fm) < WGM ? (nM - fm) : WGM;
;         u.pm = fm + ((wgid % nig) % gsz); u.pn = (wgid % nig) / gsz; return true;
;     }
; template <class Epi, class Sched, bool ALIGN_EPI = false, bool SP2 = false>
; __device__ __forceinline__ void gemm_phase(PG8_LAS unsigned char* lds, const Gemm g, const Sched& S, const Epi& E) {
;     ...
;             PG8_LDB(B0, 0, 0); PG8_LDB(B1, 0, 1); PG8_SCHED; PG8_LDA(At, 0, 0); PG8_STAGE(PG8_SA(1, 1), a1 + hstep, voffA);
.LBB0_1644:
	s_add_i32 s58, 0, 0x10000
	v_add_u32_e32 v162, s58, v165
	s_add_i32 s60, 0, 0x14000
	ds_read_b128 v[132:135], v162
	ds_read_b128 v[136:139], v162 offset:1024
	ds_read_b128 v[140:143], v162 offset:2048
	ds_read_b128 v[180:183], v162 offset:3072
	v_add_u32_e32 v162, s60, v165
	ds_read_b128 v[200:203], v162
	ds_read_b128 v[204:207], v162 offset:1024
	ds_read_b128 v[208:211], v162 offset:2048
	ds_read_b128 v[212:215], v162 offset:3072
	ds_read_b128 v[216:219], v197
	ds_read_b128 v[220:223], v197 offset:1024
	ds_read_b128 v[224:227], v197 offset:2048
	ds_read_b128 v[228:231], v197 offset:3072
	ds_read_b128 v[232:235], v197 offset:4096
	ds_read_b128 v[236:239], v197 offset:5120
	ds_read_b128 v[240:243], v197 offset:6144
	ds_read_b128 v[244:247], v197 offset:7168
	s_add_i32 s35, s35, 1
	s_mul_i32 s6, s35, s23
	s_mul_hi_u32 s7, s35, s22
	s_add_i32 s7, s7, s6
	s_mul_i32 s6, s35, s22
	s_add_u32 s6, s6, s89
	s_addc_u32 s7, s7, s13
	v_mov_b64_e32 v[0:1], 0x580
	v_cmp_lt_i64_e64 s[36:37], s[6:7], v[0:1]
	v_mov_b64_e32 v[0:1], 0x57f
	v_cmp_gt_i64_e32 vcc, s[6:7], v[0:1]
	s_cbranch_vccnz .LBB0_1646
	s_ashr_i32 s7, s6, 31
	s_lshr_b32 s7, s7, 29
	s_add_i32 s7, s6, s7
	s_ashr_i32 s39, s7, 3
	s_and_b32 s7, s7, -8
	s_sub_i32 s6, s6, s7
	s_cmp_lt_i32 s6, 0
	s_movk_i32 s7, 0xb1
	s_cselect_b32 s7, s7, 0xb0
	s_mul_i32 s6, s6, s7
	s_add_i32 s6, s6, s39
	s_mul_hi_i32 s7, s6, 0x2e8ba2e9
	s_lshr_b32 s39, s7, 31
	s_ashr_i32 s7, s7, 4
	s_add_i32 s7, s7, s39
	s_lshl_b32 s39, s7, 2
	s_sub_i32 s44, 64, s39
	s_min_i32 s45, s44, 4
	s_abs_i32 s44, s45
	v_cvt_f32_u32_e32 v0, s44
	s_sub_i32 s47, 0, s44
	s_mulk_i32 s7, 0x58
	s_sub_i32 s6, s6, s7
	v_rcp_iflag_f32_e32 v0, v0
	s_abs_i32 s7, s6
	s_xor_b32 s46, s6, s45
	s_ashr_i32 s46, s46, 31
	v_mul_f32_e32 v0, 0x4f7ffffe, v0
	v_cvt_u32_f32_e32 v0, v0
	s_nop 0
	v_readfirstlane_b32 s48, v0
	s_mul_i32 s47, s47, s48
	s_mul_hi_u32 s47, s48, s47
	s_add_i32 s48, s48, s47
	s_mul_hi_u32 s47, s7, s48
	s_mul_i32 s48, s47, s44
	s_sub_i32 s7, s7, s48
	s_add_i32 s49, s47, 1
	s_sub_i32 s48, s7, s44
	s_cmp_ge_u32 s7, s44
	s_cselect_b32 s47, s49, s47
	s_cselect_b32 s7, s48, s7
	s_add_i32 s48, s47, 1
	s_cmp_ge_u32 s7, s44
	s_cselect_b32 s7, s48, s47
	s_xor_b32 s7, s7, s46
	s_sub_i32 s44, s7, s46
	s_mul_i32 s7, s44, s45
	s_sub_i32 s6, s6, s7
	s_add_i32 s46, s39, s6

; #define PG8_STAGE(bufoff, gbase, voff) do { _Pragma("unroll") for (int _i = 0; _i < 2; ++_i) \
;         __builtin_amdgcn_global_load_lds((const unsigned*)((const char*)(gbase) + (voff)[_i]), (PG8_LAS unsigned*)(lds + (bufoff) + ldsw + _i * 8192), 16, 0, 0); } while (0)
; #define PG8_LDA(dst, b, h) do { _Pragma("unroll") for (int m = 0; m < 4; ++m) _Pragma("unroll") for (int k = 0; k < 2; ++k) dst[m][k] = *(const PG8_LAS bf16x8*)(lds + PG8_SA(b, h) + aoff + m * 2048 + k * 1024); } while (0)
; #define PG8_LDB(dst, b, h) do { _Pragma("unroll") for (int n = 0; n < 2; ++n) _Pragma("unroll") for (int k = 0; k < 2; ++k) dst[n][k] = *(const PG8_LAS bf16x8*)(lds + PG8_SB(b, h) + boff + n * 2048 + k * 1024); } while (0)
; #define PG8_MMA(ai, bj, At, Bt) do { __builtin_amdgcn_s_setprio(1); _Pragma("unroll") for (int m = 0; m < 4; ++m) _Pragma("unroll") for (int n = 0; n < 2; ++n) _Pragma("unroll") for (int k = 0; k < 2; ++k) \
;         acc[ai][bj][m][n] = __builtin_amdgcn_mfma_f32_16x16x32_bf16(Bt[n][k], At[m][k], acc[ai][bj][m][n], 0, 0, 0); __builtin_amdgcn_s_setprio(0); } while (0)
; #define PG8_WAIT_V(n) asm volatile("s_waitcnt vmcnt(" #n ")" ::: "memory")
; #define PG8_WAIT_L(n) asm volatile("s_waitcnt lgkmcnt(" #n ")" ::: "memory")
; #define PG8_BAR __builtin_amdgcn_s_barrier()
; #define PG8_SCHED __builtin_amdgcn_sched_barrier(0)
; template <class Epi, class Sched, bool ALIGN_EPI = false, bool SP2 = false>
; __device__ __forceinline__ void gemm_phase(PG8_LAS unsigned char* lds, const Gemm g, const Sched& S, const Epi& E) {
;     ...
;             if (last && has_next) S.a_ready(nxt);
;             if (last) E.pre(cur, wid, lane);
;             if constexpr (SP2) {
;             PG8_LDB(B0, 0, 0); PG8_LDB(B1, 0, 1); PG8_SCHED; PG8_LDA(At, 0, 0); PG8_STAGE(PG8_SA(1, 1), a1 + hstep, voffA);
;             PG8_WAIT_V(8); PG8_WAIT_L(0); PG8_BAR; PG8_MMA(0, 0, At, B0); PG8_MMA(0, 1, At, B1); PG8_BAR; PG8_SCHED;
.Lgu_peel:
	s_mov_b64 s[0:1], 0
	s_add_u32 s6, s4, 0xfffc0080
	s_addc_u32 s7, s5, -1
	s_and_b64 s[0:1], s[0:1], exec
	s_cselect_b32 s7, s39, s7
	s_cselect_b32 s6, s47, s6
	s_cselect_b32 s1, s53, s56
	s_cselect_b32 s0, s54, s55
	s_cmp_eq_u32 s57, -2
	s_cselect_b32 vcc_lo, 1, 0
	s_cmp_gt_u32 s35, 1
	s_cselect_b32 vcc_lo, vcc_lo, 0
	s_add_i32 s58, 0, 0x10000
	s_add_i32 s60, 0, 0x14000
	v_lshl_add_u64 v[168:169], s[4:5], 0, v[158:159]
	s_add_i32 m0, s27, 0xc000
	global_load_lds_dwordx4 v[168:169], off
	v_lshl_add_u64 v[168:169], s[4:5], 0, v[160:161]
	s_add_i32 m0, s27, 0xe000
	s_nop 0
	global_load_lds_dwordx4 v[168:169], off
	s_waitcnt vmcnt(16)
	s_cmp_lg_u32 vcc_lo, 0
	s_cbranch_scc1 .Lgu_relaxed0_p
	s_waitcnt vmcnt(8)
